# grid barrier exit trims: acquire issued before the spin, per-XCD relay word no longer written or waited on; on top of the direct top-level poll
# speedup vs baseline: 1.0032x; 1.0032x over previous
.LBB0_261:
	s_or_b64 exec, exec, s[12:13]
	v_cvt_f32_u32_e32 v5, v3
	s_waitcnt vmcnt(0)
	v_readfirstlane_b32 s2, v4
	v_sub_u32_e32 v4, 0, v3
	v_rcp_iflag_f32_e32 v5, v5
	v_add_u32_e32 v6, s2, v2
	v_mul_f32_e32 v5, 0x4f7ffffe, v5
	v_cvt_u32_f32_e32 v5, v5
	v_mul_lo_u32 v2, v4, v5
	v_mul_hi_u32 v2, v5, v2
	v_add_u32_e32 v2, v5, v2
	v_mul_hi_u32 v2, v6, v2
	v_mul_lo_u32 v4, v2, v3
	v_sub_u32_e32 v4, v6, v4
	v_add_u32_e32 v5, 1, v2
	v_cmp_ge_u32_e32 vcc, v4, v3
	s_nop 1
	v_cndmask_b32_e32 v2, v2, v5, vcc
	v_sub_u32_e32 v5, v4, v3
	v_cndmask_b32_e32 v4, v4, v5, vcc
	v_add_u32_e32 v5, 1, v2
	v_cmp_ge_u32_e32 vcc, v4, v3
	v_add_u32_e32 v4, 1, v6
	s_nop 0
	v_cndmask_b32_e32 v2, v2, v5, vcc
	v_mul_lo_u32 v5, v3, v2
	v_add_u32_e32 v3, v5, v3
	v_cmp_ne_u32_e32 vcc, v4, v3
	s_and_saveexec_b64 s[2:3], vcc
	s_xor_b64 s[10:11], exec, s[2:3]
	s_cbranch_execz .LBB0_275
	s_waitcnt lgkmcnt(0)
	buffer_inv sc1
	v_readlane_b32 s16, v255, 47
	v_mov_b32_e32 v1, 0x7000
	global_load_dword v1, v1, s[6:7] offset:1280 sc1
	v_mov_b32_e32 v2, s16
	s_add_u32 s16, s6, 0x7500
	s_addc_u32 s17, s7, 0
	s_waitcnt vmcnt(0)
	v_cmp_eq_u32_e32 vcc, v1, v2
	s_and_saveexec_b64 s[12:13], vcc
	s_cbranch_execz .LBB0_274
	s_add_u32 s14, s6, 0x4200
	s_addc_u32 s15, s7, 0
	s_mov_b32 s2, 1
	s_mov_b64 s[18:19], 0
	v_mov_b32_e32 v1, 0
	s_branch .LBB0_265

.LBB0_274:
	s_or_b64 exec, exec, s[12:13]
	s_waitcnt vmcnt(0)
	s_waitcnt vmcnt(0)

.LBB0_278:
	s_or_b64 exec, exec, s[12:13]
	v_cvt_f32_u32_e32 v4, v1
	s_waitcnt vmcnt(0)
	v_readfirstlane_b32 s2, v3
	s_add_u32 s12, s6, 0x7500
	s_addc_u32 s13, s7, 0
	v_rcp_iflag_f32_e32 v4, v4
	v_add_u32_e32 v2, s2, v2
	v_add_u32_e32 v5, 1, v2
	s_mov_b64 s[14:15], -1
	v_mul_f32_e32 v3, 0x4f7ffffe, v4
	v_cvt_u32_f32_e32 v3, v3
	v_sub_u32_e32 v4, 0, v1
	v_mul_lo_u32 v4, v4, v3
	v_mul_hi_u32 v4, v3, v4
	v_add_u32_e32 v3, v3, v4
	v_mul_hi_u32 v3, v2, v3
	v_mul_lo_u32 v4, v3, v1
	v_sub_u32_e32 v2, v2, v4
	v_add_u32_e32 v6, 1, v3
	v_cmp_ge_u32_e32 vcc, v2, v1
	v_sub_u32_e32 v4, v2, v1
	s_nop 0
	v_cndmask_b32_e32 v3, v3, v6, vcc
	v_cndmask_b32_e32 v2, v2, v4, vcc
	v_add_u32_e32 v4, 1, v3
	v_cmp_ge_u32_e32 vcc, v2, v1
	s_nop 1
	v_cndmask_b32_e32 v4, v3, v4, vcc
	v_mul_lo_u32 v2, v1, v4
	v_add_u32_e32 v1, v2, v1
	v_cmp_ne_u32_e32 vcc, v5, v1
	v_mov_b64_e32 v[2:3], s[12:13]
	s_mov_b32 s30, 0
	s_and_saveexec_b64 s[10:11], vcc
	s_cbranch_execz .LBB0_290
	s_mov_b32 s30, 1
	buffer_inv sc1
	v_mov_b32_e32 v1, 0
	global_load_dword v2, v1, s[12:13] sc1
	s_mov_b64 s[18:19], 0
	s_waitcnt vmcnt(0)
	v_cmp_eq_u32_e32 vcc, v2, v4
	s_and_saveexec_b64 s[16:17], vcc
	s_cbranch_execz .LBB0_289
	s_add_u32 s14, s6, 0x4200
	s_addc_u32 s15, s7, 0
	s_mov_b32 s2, 1
	s_mov_b64 s[6:7], 0
	s_branch .LBB0_282

.LBB0_292:
	s_or_b64 exec, exec, s[6:7]
	s_mov_b64 s[6:7], exec
	v_mbcnt_lo_u32_b32 v1, s6, 0
	v_mbcnt_hi_u32_b32 v1, s7, v1
	v_cmp_eq_u32_e32 vcc, 0, v1
	s_cmp_eq_u32 s30, 1
	s_cbranch_scc1 .Lbinv_skip_p0
	buffer_inv sc1
.Lbinv_skip_p0:
	s_and_saveexec_b64 s[10:11], vcc
	s_cbranch_execz .LBB0_294
	s_bcnt1_i32_b64 s2, s[6:7]
	v_mov_b32_e32 v1, 0x2000
	v_mov_b32_e32 v2, s2

.LBB0_1652:
	s_or_b64 exec, exec, s[12:13]
	v_cvt_f32_u32_e32 v7, v5
	s_waitcnt vmcnt(0)
	v_readfirstlane_b32 s2, v6
	v_sub_u32_e32 v6, 0, v5
	v_rcp_iflag_f32_e32 v7, v7
	v_add_u32_e32 v8, s2, v2
	v_mul_f32_e32 v7, 0x4f7ffffe, v7
	v_cvt_u32_f32_e32 v7, v7
	v_mul_lo_u32 v2, v6, v7
	v_mul_hi_u32 v2, v7, v2
	v_add_u32_e32 v2, v7, v2
	v_mul_hi_u32 v2, v8, v2
	v_mul_lo_u32 v6, v2, v5
	v_sub_u32_e32 v6, v8, v6
	v_add_u32_e32 v7, 1, v2
	v_cmp_ge_u32_e32 vcc, v6, v5
	s_nop 1
	v_cndmask_b32_e32 v2, v2, v7, vcc
	v_sub_u32_e32 v7, v6, v5
	v_cndmask_b32_e32 v6, v6, v7, vcc
	v_add_u32_e32 v7, 1, v2
	v_cmp_ge_u32_e32 vcc, v6, v5
	v_add_u32_e32 v6, 1, v8
	s_nop 0
	v_cndmask_b32_e32 v2, v2, v7, vcc
	v_mul_lo_u32 v7, v5, v2
	v_add_u32_e32 v5, v7, v5
	v_cmp_ne_u32_e32 vcc, v6, v5
	s_and_saveexec_b64 s[2:3], vcc
	s_xor_b64 s[10:11], exec, s[2:3]
	s_cbranch_execz .LBB0_1669
	s_waitcnt lgkmcnt(0)
	buffer_inv sc1
	v_readlane_b32 s16, v255, 47
	v_mov_b32_e32 v4, 0x7000
	global_load_dword v4, v4, s[6:7] offset:1280 sc1
	v_mov_b32_e32 v2, s16
	s_add_u32 s16, s6, 0x7500
	s_addc_u32 s17, s7, 0
	s_waitcnt vmcnt(0)
	v_cmp_eq_u32_e32 vcc, v4, v2
	s_and_saveexec_b64 s[12:13], vcc
	s_cbranch_execz .LBB0_1668
	s_add_u32 s14, s6, 0x4200
	s_addc_u32 s15, s7, 0
	s_mov_b32 s2, 1
	s_mov_b64 s[18:19], 0
	s_branch .LBB0_1656

.LBB0_1672:
	s_or_b64 exec, exec, s[12:13]
	s_waitcnt vmcnt(0)
	v_readfirstlane_b32 s2, v5
	v_sub_u32_e32 v6, 0, v4
	s_add_u32 s10, s6, 0x7500
	v_add_u32_e32 v5, s2, v2
	v_cvt_f32_u32_e32 v2, v4
	s_addc_u32 s11, s7, 0
	s_mov_b64 s[14:15], -1
	v_rcp_iflag_f32_e32 v2, v2
	s_nop 0
	v_mul_f32_e32 v2, 0x4f7ffffe, v2
	v_cvt_u32_f32_e32 v2, v2
	v_mul_lo_u32 v6, v6, v2
	v_mul_hi_u32 v6, v2, v6
	v_add_u32_e32 v2, v2, v6
	v_mul_hi_u32 v2, v5, v2
	v_mul_lo_u32 v6, v2, v4
	v_sub_u32_e32 v6, v5, v6
	v_cmp_ge_u32_e32 vcc, v6, v4
	v_add_u32_e32 v7, 1, v2
	v_add_u32_e32 v5, 1, v5
	v_cndmask_b32_e32 v2, v2, v7, vcc
	v_sub_u32_e32 v7, v6, v4
	v_cndmask_b32_e32 v6, v6, v7, vcc
	v_cmp_ge_u32_e32 vcc, v6, v4
	v_add_u32_e32 v6, 1, v2
	s_nop 0
	v_cndmask_b32_e32 v2, v2, v6, vcc
	v_mul_lo_u32 v6, v4, v2
	v_add_u32_e32 v4, v6, v4
	v_cmp_ne_u32_e32 vcc, v5, v4
	v_mov_b64_e32 v[4:5], s[10:11]
	s_mov_b32 s30, 0
	s_and_saveexec_b64 s[12:13], vcc
	s_cbranch_execz .LBB0_1684
	s_mov_b32 s30, 1
	buffer_inv sc1
	global_load_dword v4, v3, s[10:11] sc1
	s_mov_b64 s[18:19], 0
	s_waitcnt vmcnt(0)
	v_cmp_eq_u32_e32 vcc, v4, v2
	s_and_saveexec_b64 s[16:17], vcc
	s_cbranch_execz .LBB0_1683
	s_add_u32 s14, s6, 0x4200
	s_addc_u32 s15, s7, 0
	s_mov_b32 s2, 1
	s_mov_b64 s[6:7], 0
	s_branch .LBB0_1676

.LBB0_1686:
	s_or_b64 exec, exec, s[6:7]
	s_mov_b64 s[6:7], exec
	v_mbcnt_lo_u32_b32 v2, s6, 0
	v_mbcnt_hi_u32_b32 v2, s7, v2
	v_cmp_eq_u32_e32 vcc, 0, v2
	s_cmp_eq_u32 s30, 1
	s_cbranch_scc1 .Lbinv_skip_lp
	buffer_inv sc1
.Lbinv_skip_lp:
	s_and_saveexec_b64 s[10:11], vcc
	s_cbranch_execnz .LBB0_1687
	s_getpc_b64 s[98:99]

.LBB0_1687:
	s_bcnt1_i32_b64 s2, s[6:7]
	v_mov_b32_e32 v2, s2
	v_mov_b32_e32 v4, 0x2000
	s_getpc_b64 s[98:99]
